# NSA phase: static s_setprio 1 for waves 4-7, per-block priority toggles removed
# speedup vs baseline: 1.0036x; 1.0036x over previous
; #define LAS __attribute__((address_space(3)))
; #define P_part   WSP(float, WS_PART)
; #define P_rstd   WSP(float, WS_RSTD)
; DI int opaque_tid() { int t = threadIdx.x; asm volatile("" : "+v"(t)); return t; }
; DI void phase_nsa(const Params& P, unsigned char* smem) {
;     const int tid = opaque_tid(), lane = tid & 63, wave = __builtin_amdgcn_readfirstlane(tid >> 6);
;     LAS unsigned char* wl = (LAS unsigned char*)smem + wave * NSA_WAVE_LDS;
;     for (int tk = blockIdx.x * 512 + tid; tk < NTOK; tk += gridDim.x * 512) {
;         const f32x4* pp = (const f32x4*)(P_part + (size_t)tk * 64); float s = 0.f;
; #pragma unroll
;         for (int j = 0; j < 16; ++j) { const f32x4 v = pp[j]; s += (v[0] + v[1]) + (v[2] + v[3]); }
;         P_rstd[tk] = 1.f / sqrtf(s * (1.f / 2048.f) + EPSF);
;     }
.LBB0_373:
	s_or_b64 exec, exec, s[2:3]
	v_mov_b32_e32 v146, v215
	v_readfirstlane_b32 s89, v215
	s_cmpk_lt_u32 s89, 0x100
	s_cbranch_scc1 .Lnsa_prio_done
	s_setprio 1
.Lnsa_prio_done:
	s_waitcnt lgkmcnt(0)
	s_barrier
	s_mov_b32 s0, 0x8000
	v_lshl_add_u32 v0, s6, 9, v146
	v_cmp_gt_i32_e32 vcc, s0, v0
	s_and_saveexec_b64 s[4:5], vcc
	s_cbranch_execz .LBB0_376
	s_add_u32 s8, s30, 0x3ef12000
	s_addc_u32 s9, s31, 0
	s_add_u32 s16, s30, 0x3f712000
	s_addc_u32 s17, s31, 0
	s_lshl_b32 s20, s10, 9
	s_mov_b64 s[18:19], 0
	v_mov_b32_e32 v2, 0x358637bd
	s_mov_b32 s21, 0xf800000
	v_mov_b32_e32 v3, 0x260
	s_movk_i32 s22, 0x7fff

; #define LAS __attribute__((address_space(3)))
; #define MFMA32(a, b, c) __builtin_amdgcn_mfma_f32_32x32x16_bf16((a), (b), (c), 0, 0, 0)
; DI bf16x8 cat44(s16x4 a, s16x4 b) { return __builtin_shufflevector(a, b, 0, 1, 2, 3, 4, 5, 6, 7); }
; template <int MODE>
; DI void co_finish(f32x16 S, LAS unsigned char* st, int key_base, AttnState& as, int tq, bool rowsel, int vb_in, int hh) {
;     ...
;     as.l += ps; as.m = mnew;
;     const bf16x8 p0 = pack8(S, 0), p1 = pack8(S, 1);
;     __builtin_amdgcn_s_setprio(1);
; #pragma unroll
;     for (int dt = 0; dt < 4; ++dt) {
;         LAS unsigned char* vp = st + 2048 * dt;
;         const bf16x8 a0 = cat44(*(const LAS s16x4*)(vp + (vb ^ 0)), *(const LAS s16x4*)(vp + (vb ^ 16))), a1 = cat44(*(const LAS s16x4*)(vp + (vb ^ 32)), *(const LAS s16x4*)(vp + (vb ^ 48)));
;         as.acc[dt] = MFMA32(a0, p0, as.acc[dt]); as.acc[dt] = MFMA32(a1, p1, as.acc[dt]);
;     }
;     __builtin_amdgcn_s_setprio(0);
.LBB0_378:
	v_add_f32_e32 v17, v17, v18
	v_add_f32_e32 v163, v17, v163
	v_cvt_pk_bf16_f32 v2, v0, v2
	v_cvt_pk_bf16_f32 v3, v3, v4
	v_cvt_pk_bf16_f32 v4, v5, v6
	v_cvt_pk_bf16_f32 v5, v7, v8
	v_cvt_pk_bf16_f32 v6, v9, v10
	v_cvt_pk_bf16_f32 v7, v11, v12
	v_cvt_pk_bf16_f32 v8, v13, v14
	v_cvt_pk_bf16_f32 v9, v15, v16
	v_add_u32_e32 v0, s62, v156
	v_xad_u32 v30, v156, 16, s62
	ds_read2st64_b64 v[10:13], v0 offset0:16 offset1:20
	ds_read2st64_b64 v[14:17], v30 offset0:16 offset1:20
	v_xad_u32 v31, v156, 32, s62
	v_xad_u32 v100, v156, 48, s62
	ds_read2st64_b64 v[22:25], v31 offset0:16 offset1:20
	ds_read2st64_b64 v[26:29], v100 offset0:16 offset1:20
	s_waitcnt lgkmcnt(0)
	v_mov_b32_e32 v20, v14
	v_mov_b32_e32 v21, v15
	v_mov_b32_e32 v14, v12
	v_mov_b32_e32 v15, v13
	v_mov_b32_e32 v18, v10
	v_mov_b32_e32 v19, v11
	v_mfma_f32_32x32x16_bf16 v[64:79], v[14:17], v[2:5], v[64:79]
	ds_read2st64_b64 v[10:13], v0 offset0:24 offset1:28
	ds_read2st64_b64 v[14:17], v30 offset0:24 offset1:28
	v_mov_b32_e32 v98, v26
	v_mov_b32_e32 v99, v27
	v_mov_b32_e32 v26, v24
	v_mov_b32_e32 v27, v25
	v_mov_b32_e32 v96, v22
	v_mov_b32_e32 v97, v23
	v_mfma_f32_32x32x16_bf16 v[80:95], v[18:21], v[2:5], v[80:95]
	s_waitcnt lgkmcnt(0)
	v_mov_b32_e32 v18, v10
	v_mov_b32_e32 v19, v11
	v_mov_b32_e32 v20, v14
	v_mov_b32_e32 v21, v15
	v_mov_b32_e32 v14, v12
	v_mov_b32_e32 v15, v13
	ds_read2st64_b64 v[22:25], v31 offset0:24 offset1:28
	v_mfma_f32_32x32x16_bf16 v[64:79], v[26:29], v[6:9], v[64:79]
	ds_read2st64_b64 v[26:29], v100 offset0:24 offset1:28
	v_mfma_f32_32x32x16_bf16 v[48:63], v[18:21], v[2:5], v[48:63]
	v_mfma_f32_32x32x16_bf16 v[32:47], v[14:17], v[2:5], v[32:47]
	v_mfma_f32_32x32x16_bf16 v[80:95], v[96:99], v[6:9], v[80:95]
	s_waitcnt lgkmcnt(0)
	v_mov_b32_e32 v96, v22
	v_mov_b32_e32 v97, v23
	v_mov_b32_e32 v98, v26
	v_mov_b32_e32 v99, v27
	v_mov_b32_e32 v26, v24
	v_mov_b32_e32 v27, v25
	v_mfma_f32_32x32x16_bf16 v[48:63], v[96:99], v[6:9], v[48:63]
	s_nop 0
	v_mfma_f32_32x32x16_bf16 v[32:47], v[26:29], v[6:9], v[32:47]

; #define LAS __attribute__((address_space(3)))
; #define MFMA32(a, b, c) __builtin_amdgcn_mfma_f32_32x32x16_bf16((a), (b), (c), 0, 0, 0)
; DI f32x16 co_qk1(LAS unsigned char* st, const bf16x8 (&qf)[8], int ka_in) {
;     const int ka = ka_in;
;     f32x16 S;
; #pragma unroll
;     for (int i = 0; i < 16; ++i) S[i] = 0.f;
;     __builtin_amdgcn_s_setprio(1);
; #pragma unroll
;     for (int ks = 0; ks < 8; ++ks) { const bf16x8 a = *(const LAS bf16x8*)(st + (ka ^ (32 * ks))); S = MFMA32(a, qf[ks], S); }
;     __builtin_amdgcn_s_setprio(0);
;     return S;
; }
.LBB0_422:
	s_cmp_le_i32 s77, s59
	s_cselect_b64 s[4:5], -1, 0
	s_and_b32 s0, s78, 0xc000
	s_add_i32 s16, s0, 0
	s_cmp_gt_i32 s77, s59
	s_cbranch_scc1 .LBB0_424
	s_andn2_b64 vcc, exec, s[8:9]
	s_cbranch_vccz .Lfs_cmp
	v_add_u32_e32 v0, s16, v162
	ds_read_b128 v[2:5], v0
	v_add_u32_e32 v0, s16, v164
	ds_read_b128 v[6:9], v0
	v_add_u32_e32 v0, s16, v165
	s_waitcnt lgkmcnt(0)
	v_mfma_f32_32x32x16_bf16 v[96:111], v[2:5], v[112:115], 0
	ds_read_b128 v[2:5], v0
	v_add_u32_e32 v0, s16, v166
	v_mfma_f32_32x32x16_bf16 v[96:111], v[6:9], v[116:119], v[96:111]
	ds_read_b128 v[6:9], v0
	v_add_u32_e32 v0, s16, v167
	s_waitcnt lgkmcnt(0)
	v_mfma_f32_32x32x16_bf16 v[96:111], v[2:5], v[120:123], v[96:111]
	ds_read_b128 v[2:5], v0
	v_add_u32_e32 v0, s16, v168
	v_mfma_f32_32x32x16_bf16 v[96:111], v[6:9], v[124:127], v[96:111]
	ds_read_b128 v[6:9], v0
	v_add_u32_e32 v0, s16, v169
	s_waitcnt lgkmcnt(0)
	v_mfma_f32_32x32x16_bf16 v[96:111], v[2:5], v[128:131], v[96:111]
	ds_read_b128 v[2:5], v0
	v_add_u32_e32 v0, s16, v170
	v_mfma_f32_32x32x16_bf16 v[96:111], v[6:9], v[132:135], v[96:111]
	ds_read_b128 v[6:9], v0
	s_waitcnt lgkmcnt(0)
	v_mfma_f32_32x32x16_bf16 v[96:111], v[2:5], v[136:139], v[96:111]
	v_mfma_f32_32x32x16_bf16 v[96:111], v[6:9], v[140:143], v[96:111]

; #define LAS __attribute__((address_space(3)))
; #define MFMA32(a, b, c) __builtin_amdgcn_mfma_f32_32x32x16_bf16((a), (b), (c), 0, 0, 0)
; DI bf16x8 cat44(s16x4 a, s16x4 b) { return __builtin_shufflevector(a, b, 0, 1, 2, 3, 4, 5, 6, 7); }
; template <int MODE>
; DI void co_finish(f32x16 S, LAS unsigned char* st, int key_base, AttnState& as, int tq, bool rowsel, int vb_in, int hh) {
;     ...
;     as.l += ps; as.m = mnew;
;     const bf16x8 p0 = pack8(S, 0), p1 = pack8(S, 1);
;     __builtin_amdgcn_s_setprio(1);
; #pragma unroll
;     for (int dt = 0; dt < 4; ++dt) {
;         LAS unsigned char* vp = st + 2048 * dt;
;         const bf16x8 a0 = cat44(*(const LAS s16x4*)(vp + (vb ^ 0)), *(const LAS s16x4*)(vp + (vb ^ 16))), a1 = cat44(*(const LAS s16x4*)(vp + (vb ^ 32)), *(const LAS s16x4*)(vp + (vb ^ 48)));
;         as.acc[dt] = MFMA32(a0, p0, as.acc[dt]); as.acc[dt] = MFMA32(a1, p1, as.acc[dt]);
;     }
;     __builtin_amdgcn_s_setprio(0);
.LBB0_427:
	v_add_f32_e32 v181, v184, v185
	v_add_f32_e32 v179, v181, v179
	v_cvt_pk_bf16_f32 v184, v0, v3
	v_cvt_pk_bf16_f32 v185, v4, v5
	v_cvt_pk_bf16_f32 v186, v6, v7
	v_cvt_pk_bf16_f32 v187, v8, v9
	v_cvt_pk_bf16_f32 v4, v10, v11
	v_cvt_pk_bf16_f32 v5, v12, v13
	v_cvt_pk_bf16_f32 v6, v14, v15
	v_cvt_pk_bf16_f32 v7, v182, v183
	v_add_u32_e32 v0, s62, v156
	v_add_u32_e32 v3, s62, v171
	ds_read2st64_b64 v[8:11], v0 offset0:16 offset1:20
	ds_read2st64_b64 v[12:15], v3 offset0:16 offset1:20
	v_add_u32_e32 v181, s62, v172
	v_add_u32_e32 v182, s62, v173
	ds_read2st64_b64 v[192:195], v181 offset0:16 offset1:20
	ds_read2st64_b64 v[196:199], v182 offset0:16 offset1:20
	s_waitcnt lgkmcnt(0)
	v_mov_b32_e32 v190, v12
	v_mov_b32_e32 v191, v13
	v_mov_b32_e32 v12, v10
	v_mov_b32_e32 v13, v11
	v_mov_b32_e32 v188, v8
	v_mov_b32_e32 v189, v9
	v_mfma_f32_32x32x16_bf16 v[64:79], v[12:15], v[184:187], v[64:79]
	ds_read2st64_b64 v[8:11], v0 offset0:24 offset1:28
	ds_read2st64_b64 v[12:15], v3 offset0:24 offset1:28
	v_mov_b32_e32 v202, v196
	v_mov_b32_e32 v203, v197
	v_mov_b32_e32 v196, v194
	v_mov_b32_e32 v197, v195
	v_mov_b32_e32 v200, v192
	v_mov_b32_e32 v201, v193
	v_mfma_f32_32x32x16_bf16 v[80:95], v[188:191], v[184:187], v[80:95]
	s_waitcnt lgkmcnt(0)
	v_mov_b32_e32 v188, v8
	v_mov_b32_e32 v189, v9
	v_mov_b32_e32 v190, v12
	v_mov_b32_e32 v191, v13
	v_mov_b32_e32 v12, v10
	v_mov_b32_e32 v13, v11
	ds_read2st64_b64 v[192:195], v181 offset0:24 offset1:28
	v_mfma_f32_32x32x16_bf16 v[64:79], v[196:199], v[4:7], v[64:79]
	ds_read2st64_b64 v[196:199], v182 offset0:24 offset1:28
	v_mfma_f32_32x32x16_bf16 v[48:63], v[188:191], v[184:187], v[48:63]
	v_mfma_f32_32x32x16_bf16 v[32:47], v[12:15], v[184:187], v[32:47]
	v_mfma_f32_32x32x16_bf16 v[80:95], v[200:203], v[4:7], v[80:95]
	s_waitcnt lgkmcnt(0)
	v_mov_b32_e32 v200, v192
	v_mov_b32_e32 v201, v193
	v_mov_b32_e32 v202, v196
	v_mov_b32_e32 v203, v197
	v_mov_b32_e32 v196, v194
	v_mov_b32_e32 v197, v195
	v_mfma_f32_32x32x16_bf16 v[48:63], v[200:203], v[4:7], v[48:63]
	s_nop 0
	v_mfma_f32_32x32x16_bf16 v[32:47], v[196:199], v[4:7], v[32:47]
	s_andn2_b64 vcc, exec, s[4:5]
	s_cbranch_vccz .LBB0_429
	s_branch .LBB0_430

; #define LAS __attribute__((address_space(3)))
; #define MFMA32(a, b, c) __builtin_amdgcn_mfma_f32_32x32x16_bf16((a), (b), (c), 0, 0, 0)
; DI bf16x8 cat44(s16x4 a, s16x4 b) { return __builtin_shufflevector(a, b, 0, 1, 2, 3, 4, 5, 6, 7); }
; template <int MODE>
; DI void co_finish(f32x16 S, LAS unsigned char* st, int key_base, AttnState& as, int tq, bool rowsel, int vb_in, int hh) {
;     ...
;     as.l += ps; as.m = mnew;
;     const bf16x8 p0 = pack8(S, 0), p1 = pack8(S, 1);
;     __builtin_amdgcn_s_setprio(1);
; #pragma unroll
;     for (int dt = 0; dt < 4; ++dt) {
;         LAS unsigned char* vp = st + 2048 * dt;
;         const bf16x8 a0 = cat44(*(const LAS s16x4*)(vp + (vb ^ 0)), *(const LAS s16x4*)(vp + (vb ^ 16))), a1 = cat44(*(const LAS s16x4*)(vp + (vb ^ 32)), *(const LAS s16x4*)(vp + (vb ^ 48)));
;         as.acc[dt] = MFMA32(a0, p0, as.acc[dt]); as.acc[dt] = MFMA32(a1, p1, as.acc[dt]);
;     }
;     __builtin_amdgcn_s_setprio(0);
.LBB0_435:
	v_add_f32_e32 v2, v99, v100
	v_add_f32_e32 v179, v2, v179
	v_cvt_pk_bf16_f32 v2, v3, v4
	v_cvt_pk_bf16_f32 v3, v5, v6
	v_cvt_pk_bf16_f32 v4, v7, v8
	v_cvt_pk_bf16_f32 v5, v9, v10
	v_cvt_pk_bf16_f32 v6, v11, v12
	v_cvt_pk_bf16_f32 v7, v13, v14
	v_cvt_pk_bf16_f32 v8, v15, v96
	v_cvt_pk_bf16_f32 v9, v97, v98
	v_add_u32_e32 v14, s62, v156
	v_xad_u32 v15, v156, 16, s62
	ds_read2st64_b64 v[10:13], v14 offset0:16 offset1:20
	ds_read2st64_b64 v[96:99], v15 offset0:16 offset1:20
	v_xad_u32 v157, v156, 32, s62
	v_xad_u32 v184, v156, 48, s62
	ds_read2st64_b64 v[104:107], v157 offset0:16 offset1:20
	ds_read2st64_b64 v[108:111], v184 offset0:16 offset1:20
	s_waitcnt lgkmcnt(0)
	v_mov_b32_e32 v102, v96
	v_mov_b32_e32 v103, v97
	v_mov_b32_e32 v96, v12
	v_mov_b32_e32 v97, v13
	v_mov_b32_e32 v100, v10
	v_mov_b32_e32 v101, v11
	v_mfma_f32_32x32x16_bf16 v[64:79], v[96:99], v[2:5], v[64:79]
	ds_read2st64_b64 v[10:13], v14 offset0:24 offset1:28
	ds_read2st64_b64 v[96:99], v15 offset0:24 offset1:28
	v_mov_b32_e32 v182, v108
	v_mov_b32_e32 v183, v109
	v_mov_b32_e32 v108, v106
	v_mov_b32_e32 v109, v107
	v_mov_b32_e32 v180, v104
	v_mov_b32_e32 v181, v105
	v_mfma_f32_32x32x16_bf16 v[80:95], v[100:103], v[2:5], v[80:95]
	s_waitcnt lgkmcnt(0)
	v_mov_b32_e32 v100, v10
	v_mov_b32_e32 v101, v11
	v_mov_b32_e32 v102, v96
	v_mov_b32_e32 v103, v97
	v_mov_b32_e32 v96, v12
	v_mov_b32_e32 v97, v13
	ds_read2st64_b64 v[104:107], v157 offset0:24 offset1:28
	v_mfma_f32_32x32x16_bf16 v[64:79], v[108:111], v[6:9], v[64:79]
	ds_read2st64_b64 v[108:111], v184 offset0:24 offset1:28
	v_mfma_f32_32x32x16_bf16 v[48:63], v[100:103], v[2:5], v[48:63]
	v_mfma_f32_32x32x16_bf16 v[32:47], v[96:99], v[2:5], v[32:47]
	v_mfma_f32_32x32x16_bf16 v[80:95], v[180:183], v[6:9], v[80:95]
	s_waitcnt lgkmcnt(0)
	v_mov_b32_e32 v180, v104
	v_mov_b32_e32 v181, v105
	v_mov_b32_e32 v182, v108
	v_mov_b32_e32 v183, v109
	v_mov_b32_e32 v108, v106
	v_mov_b32_e32 v109, v107
	v_mfma_f32_32x32x16_bf16 v[48:63], v[180:183], v[6:9], v[48:63]
	s_nop 0
	v_mfma_f32_32x32x16_bf16 v[32:47], v[108:111], v[6:9], v[32:47]
	s_branch .LBB0_438

; #define LAS __attribute__((address_space(3)))
; #define MFMA32(a, b, c) __builtin_amdgcn_mfma_f32_32x32x16_bf16((a), (b), (c), 0, 0, 0)
; DI f32x16 co_qk1(LAS unsigned char* st, const bf16x8 (&qf)[8], int ka_in) {
;     const int ka = ka_in;
;     f32x16 S;
; #pragma unroll
;     for (int i = 0; i < 16; ++i) S[i] = 0.f;
;     __builtin_amdgcn_s_setprio(1);
; #pragma unroll
;     for (int ks = 0; ks < 8; ++ks) { const bf16x8 a = *(const LAS bf16x8*)(st + (ka ^ (32 * ks))); S = MFMA32(a, qf[ks], S); }
;     __builtin_amdgcn_s_setprio(0);
;     return S;
; }
.Lfast_win_orig:
	v_add_u32_e32 v0, s16, v162
	ds_read_b128 v[2:5], v0
	v_add_u32_e32 v0, s16, v164
	ds_read_b128 v[6:9], v0
	v_add_u32_e32 v0, s16, v165
	s_waitcnt lgkmcnt(0)
	v_mfma_f32_32x32x16_bf16 v[96:111], v[2:5], v[112:115], 0
	ds_read_b128 v[2:5], v0
	v_add_u32_e32 v0, s16, v166
	v_mfma_f32_32x32x16_bf16 v[96:111], v[6:9], v[116:119], v[96:111]
	ds_read_b128 v[6:9], v0
	v_add_u32_e32 v0, s16, v167
	s_waitcnt lgkmcnt(0)
	v_mfma_f32_32x32x16_bf16 v[96:111], v[2:5], v[120:123], v[96:111]
	ds_read_b128 v[2:5], v0
	v_add_u32_e32 v0, s16, v168
	v_mfma_f32_32x32x16_bf16 v[96:111], v[6:9], v[124:127], v[96:111]
	ds_read_b128 v[6:9], v0
	v_add_u32_e32 v0, s16, v169
	s_waitcnt lgkmcnt(0)
	v_mfma_f32_32x32x16_bf16 v[96:111], v[2:5], v[128:131], v[96:111]
	ds_read_b128 v[2:5], v0
	v_add_u32_e32 v0, s16, v170
	v_mfma_f32_32x32x16_bf16 v[96:111], v[6:9], v[132:135], v[96:111]
	ds_read_b128 v[6:9], v0
	s_waitcnt lgkmcnt(0)
	v_mfma_f32_32x32x16_bf16 v[96:111], v[2:5], v[136:139], v[96:111]
	v_mfma_f32_32x32x16_bf16 v[96:111], v[6:9], v[140:143], v[96:111]

; #define LAS __attribute__((address_space(3)))
; #define MFMA32(a, b, c) __builtin_amdgcn_mfma_f32_32x32x16_bf16((a), (b), (c), 0, 0, 0)
; DI bf16x8 cat44(s16x4 a, s16x4 b) { return __builtin_shufflevector(a, b, 0, 1, 2, 3, 4, 5, 6, 7); }
; template <int MODE>
; DI void co_finish(f32x16 S, LAS unsigned char* st, int key_base, AttnState& as, int tq, bool rowsel, int vb_in, int hh) {
;     ...
;     as.l += ps; as.m = mnew;
;     const bf16x8 p0 = pack8(S, 0), p1 = pack8(S, 1);
;     __builtin_amdgcn_s_setprio(1);
; #pragma unroll
;     for (int dt = 0; dt < 4; ++dt) {
;         LAS unsigned char* vp = st + 2048 * dt;
;         const bf16x8 a0 = cat44(*(const LAS s16x4*)(vp + (vb ^ 0)), *(const LAS s16x4*)(vp + (vb ^ 16))), a1 = cat44(*(const LAS s16x4*)(vp + (vb ^ 32)), *(const LAS s16x4*)(vp + (vb ^ 48)));
;         as.acc[dt] = MFMA32(a0, p0, as.acc[dt]); as.acc[dt] = MFMA32(a1, p1, as.acc[dt]);
;     }
;     __builtin_amdgcn_s_setprio(0);
.LBB0_520:
	v_add_f32_e32 v177, v179, v180
	v_add_f32_e32 v175, v177, v175
	v_cvt_pk_bf16_f32 v2, v0, v2
	v_cvt_pk_bf16_f32 v3, v3, v4
	v_cvt_pk_bf16_f32 v4, v5, v6
	v_cvt_pk_bf16_f32 v5, v7, v8
	v_cvt_pk_bf16_f32 v6, v9, v10
	v_cvt_pk_bf16_f32 v7, v11, v12
	v_cvt_pk_bf16_f32 v8, v13, v14
	v_cvt_pk_bf16_f32 v9, v15, v178
	v_add_u32_e32 v0, s62, v156
	v_add_u32_e32 v14, s62, v171
	ds_read2st64_b64 v[10:13], v0 offset0:16 offset1:20
	ds_read2st64_b64 v[178:181], v14 offset0:16 offset1:20
	v_add_u32_e32 v15, s62, v172
	v_add_u32_e32 v177, s62, v173
	ds_read2st64_b64 v[186:189], v15 offset0:16 offset1:20
	ds_read2st64_b64 v[190:193], v177 offset0:16 offset1:20
	s_waitcnt lgkmcnt(0)
	v_mov_b32_e32 v184, v178
	v_mov_b32_e32 v185, v179
	v_mov_b32_e32 v178, v12
	v_mov_b32_e32 v179, v13
	v_mov_b32_e32 v182, v10
	v_mov_b32_e32 v183, v11
	v_mfma_f32_32x32x16_bf16 v[64:79], v[178:181], v[2:5], v[64:79]
	ds_read2st64_b64 v[10:13], v0 offset0:24 offset1:28
	ds_read2st64_b64 v[178:181], v14 offset0:24 offset1:28
	v_mov_b32_e32 v196, v190
	v_mov_b32_e32 v197, v191
	v_mov_b32_e32 v190, v188
	v_mov_b32_e32 v191, v189
	v_mov_b32_e32 v194, v186
	v_mov_b32_e32 v195, v187
	v_mfma_f32_32x32x16_bf16 v[80:95], v[182:185], v[2:5], v[80:95]
	s_waitcnt lgkmcnt(0)
	v_mov_b32_e32 v182, v10
	v_mov_b32_e32 v183, v11
	v_mov_b32_e32 v184, v178
	v_mov_b32_e32 v185, v179
	v_mov_b32_e32 v178, v12
	v_mov_b32_e32 v179, v13
	ds_read2st64_b64 v[186:189], v15 offset0:24 offset1:28
	v_mfma_f32_32x32x16_bf16 v[64:79], v[190:193], v[6:9], v[64:79]
	ds_read2st64_b64 v[190:193], v177 offset0:24 offset1:28
	v_mfma_f32_32x32x16_bf16 v[48:63], v[182:185], v[2:5], v[48:63]
	v_mfma_f32_32x32x16_bf16 v[32:47], v[178:181], v[2:5], v[32:47]
	v_mfma_f32_32x32x16_bf16 v[80:95], v[194:197], v[6:9], v[80:95]
	s_waitcnt lgkmcnt(0)
	v_mov_b32_e32 v194, v186
	v_mov_b32_e32 v195, v187
	v_mov_b32_e32 v196, v190
	v_mov_b32_e32 v197, v191
	v_mov_b32_e32 v190, v188
	v_mov_b32_e32 v191, v189
	v_mfma_f32_32x32x16_bf16 v[48:63], v[194:197], v[6:9], v[48:63]
	s_nop 0
	v_mfma_f32_32x32x16_bf16 v[32:47], v[190:193], v[6:9], v[32:47]
	s_and_b64 vcc, exec, s[2:3]
	s_cbranch_vccz .LBB0_522
	s_branch .LBB0_523

; #define LAS __attribute__((address_space(3)))
; #define MFMA32(a, b, c) __builtin_amdgcn_mfma_f32_32x32x16_bf16((a), (b), (c), 0, 0, 0)
; DI bf16x8 cat44(s16x4 a, s16x4 b) { return __builtin_shufflevector(a, b, 0, 1, 2, 3, 4, 5, 6, 7); }
; template <int MODE>
; DI void co_finish(f32x16 S, LAS unsigned char* st, int key_base, AttnState& as, int tq, bool rowsel, int vb_in, int hh) {
;     ...
;     as.l += ps; as.m = mnew;
;     const bf16x8 p0 = pack8(S, 0), p1 = pack8(S, 1);
;     __builtin_amdgcn_s_setprio(1);
; #pragma unroll
;     for (int dt = 0; dt < 4; ++dt) {
;         LAS unsigned char* vp = st + 2048 * dt;
;         const bf16x8 a0 = cat44(*(const LAS s16x4*)(vp + (vb ^ 0)), *(const LAS s16x4*)(vp + (vb ^ 16))), a1 = cat44(*(const LAS s16x4*)(vp + (vb ^ 32)), *(const LAS s16x4*)(vp + (vb ^ 48)));
;         as.acc[dt] = MFMA32(a0, p0, as.acc[dt]); as.acc[dt] = MFMA32(a1, p1, as.acc[dt]);
;     }
;     __builtin_amdgcn_s_setprio(0);
.LBB0_529:
	v_add_f32_e32 v97, v97, v98
	v_add_f32_e32 v175, v97, v175
	v_cvt_pk_bf16_f32 v2, v0, v2
	v_cvt_pk_bf16_f32 v3, v3, v4
	v_cvt_pk_bf16_f32 v4, v5, v6
	v_cvt_pk_bf16_f32 v5, v7, v8
	v_cvt_pk_bf16_f32 v6, v9, v10
	v_cvt_pk_bf16_f32 v7, v11, v12
	v_cvt_pk_bf16_f32 v8, v13, v14
	v_cvt_pk_bf16_f32 v9, v15, v96
	v_add_u32_e32 v0, s62, v156
	v_xad_u32 v14, v156, 16, s62
	ds_read2st64_b64 v[10:13], v0 offset0:16 offset1:20
	ds_read2st64_b64 v[96:99], v14 offset0:16 offset1:20
	v_xad_u32 v15, v156, 32, s62
	v_xad_u32 v180, v156, 48, s62
	ds_read2st64_b64 v[104:107], v15 offset0:16 offset1:20
	ds_read2st64_b64 v[108:111], v180 offset0:16 offset1:20
	s_waitcnt lgkmcnt(0)
	v_mov_b32_e32 v102, v96
	v_mov_b32_e32 v103, v97
	v_mov_b32_e32 v96, v12
	v_mov_b32_e32 v97, v13
	v_mov_b32_e32 v100, v10
	v_mov_b32_e32 v101, v11
	v_mfma_f32_32x32x16_bf16 v[64:79], v[96:99], v[2:5], v[64:79]
	ds_read2st64_b64 v[10:13], v0 offset0:24 offset1:28
	ds_read2st64_b64 v[96:99], v14 offset0:24 offset1:28
	v_mov_b32_e32 v178, v108
	v_mov_b32_e32 v179, v109
	v_mov_b32_e32 v108, v106
	v_mov_b32_e32 v109, v107
	v_mov_b32_e32 v176, v104
	v_mov_b32_e32 v177, v105
	v_mfma_f32_32x32x16_bf16 v[80:95], v[100:103], v[2:5], v[80:95]
	s_waitcnt lgkmcnt(0)
	v_mov_b32_e32 v100, v10
	v_mov_b32_e32 v101, v11
	v_mov_b32_e32 v102, v96
	v_mov_b32_e32 v103, v97
	v_mov_b32_e32 v96, v12
	v_mov_b32_e32 v97, v13
	ds_read2st64_b64 v[104:107], v15 offset0:24 offset1:28
	v_mfma_f32_32x32x16_bf16 v[64:79], v[108:111], v[6:9], v[64:79]
	ds_read2st64_b64 v[108:111], v180 offset0:24 offset1:28
	v_mfma_f32_32x32x16_bf16 v[48:63], v[100:103], v[2:5], v[48:63]
	v_mfma_f32_32x32x16_bf16 v[32:47], v[96:99], v[2:5], v[32:47]
	v_mfma_f32_32x32x16_bf16 v[80:95], v[176:179], v[6:9], v[80:95]
	s_waitcnt lgkmcnt(0)
	v_mov_b32_e32 v176, v104
	v_mov_b32_e32 v177, v105
	v_mov_b32_e32 v178, v108
	v_mov_b32_e32 v179, v109
	v_mov_b32_e32 v108, v106
	v_mov_b32_e32 v109, v107
	v_mfma_f32_32x32x16_bf16 v[48:63], v[176:179], v[6:9], v[48:63]
	s_nop 0
	v_mfma_f32_32x32x16_bf16 v[32:47], v[108:111], v[6:9], v[32:47]

; #define LAS __attribute__((address_space(3)))
; #define MFMA32(a, b, c) __builtin_amdgcn_mfma_f32_32x32x16_bf16((a), (b), (c), 0, 0, 0)
; DI f32x16 co_qk1(LAS unsigned char* st, const bf16x8 (&qf)[8], int ka_in) {
;     const int ka = ka_in;
;     f32x16 S;
; #pragma unroll
;     for (int i = 0; i < 16; ++i) S[i] = 0.f;
;     __builtin_amdgcn_s_setprio(1);
; #pragma unroll
;     for (int ks = 0; ks < 8; ++ks) { const bf16x8 a = *(const LAS bf16x8*)(st + (ka ^ (32 * ks))); S = MFMA32(a, qf[ks], S); }
;     __builtin_amdgcn_s_setprio(0);
;     return S;
; }
.Lfast_sel_orig:
	v_add_u32_e32 v0, s40, v162
	ds_read_b128 v[2:5], v0
	v_add_u32_e32 v0, s40, v164
	ds_read_b128 v[6:9], v0
	v_add_u32_e32 v0, s40, v165
	s_waitcnt lgkmcnt(0)
	v_mfma_f32_32x32x16_bf16 v[96:111], v[2:5], v[112:115], 0
	ds_read_b128 v[2:5], v0
	v_add_u32_e32 v0, s40, v166
	v_mfma_f32_32x32x16_bf16 v[96:111], v[6:9], v[116:119], v[96:111]
	ds_read_b128 v[6:9], v0
	v_add_u32_e32 v0, s40, v167
	s_waitcnt lgkmcnt(0)
	v_mfma_f32_32x32x16_bf16 v[96:111], v[2:5], v[120:123], v[96:111]
	ds_read_b128 v[2:5], v0
	v_add_u32_e32 v0, s40, v168
	v_mfma_f32_32x32x16_bf16 v[96:111], v[6:9], v[124:127], v[96:111]
	ds_read_b128 v[6:9], v0
	v_add_u32_e32 v0, s40, v169
	s_waitcnt lgkmcnt(0)
	v_mfma_f32_32x32x16_bf16 v[96:111], v[2:5], v[128:131], v[96:111]
	ds_read_b128 v[2:5], v0
	v_add_u32_e32 v0, s40, v170
	v_mfma_f32_32x32x16_bf16 v[96:111], v[6:9], v[132:135], v[96:111]
	ds_read_b128 v[6:9], v0
	s_waitcnt lgkmcnt(0)
	v_mfma_f32_32x32x16_bf16 v[96:111], v[2:5], v[136:139], v[96:111]
	v_mfma_f32_32x32x16_bf16 v[96:111], v[6:9], v[140:143], v[96:111]

; #define LAS __attribute__((address_space(3)))
; #define MFMA32(a, b, c) __builtin_amdgcn_mfma_f32_32x32x16_bf16((a), (b), (c), 0, 0, 0)
; DI bf16x8 cat44(s16x4 a, s16x4 b) { return __builtin_shufflevector(a, b, 0, 1, 2, 3, 4, 5, 6, 7); }
; template <int MODE>
; DI void co_finish(f32x16 S, LAS unsigned char* st, int key_base, AttnState& as, int tq, bool rowsel, int vb_in, int hh) {
;     ...
;     as.l += ps; as.m = mnew;
;     const bf16x8 p0 = pack8(S, 0), p1 = pack8(S, 1);
;     __builtin_amdgcn_s_setprio(1);
; #pragma unroll
;     for (int dt = 0; dt < 4; ++dt) {
;         LAS unsigned char* vp = st + 2048 * dt;
;         const bf16x8 a0 = cat44(*(const LAS s16x4*)(vp + (vb ^ 0)), *(const LAS s16x4*)(vp + (vb ^ 16))), a1 = cat44(*(const LAS s16x4*)(vp + (vb ^ 32)), *(const LAS s16x4*)(vp + (vb ^ 48)));
;         as.acc[dt] = MFMA32(a0, p0, as.acc[dt]); as.acc[dt] = MFMA32(a1, p1, as.acc[dt]);
;     }
;     __builtin_amdgcn_s_setprio(0);
.LBB0_551:
	v_add_f32_e32 v175, v177, v178
	v_add_f32_e32 v163, v175, v163
	v_cvt_pk_bf16_f32 v2, v0, v2
	v_cvt_pk_bf16_f32 v3, v3, v4
	v_cvt_pk_bf16_f32 v4, v5, v6
	v_cvt_pk_bf16_f32 v5, v7, v8
	v_cvt_pk_bf16_f32 v6, v9, v10
	v_cvt_pk_bf16_f32 v7, v11, v12
	v_cvt_pk_bf16_f32 v8, v13, v14
	v_cvt_pk_bf16_f32 v9, v15, v176
	v_add_u32_e32 v0, s62, v156
	v_add_u32_e32 v14, s62, v171
	ds_read2st64_b64 v[10:13], v0 offset0:16 offset1:20
	ds_read2st64_b64 v[176:179], v14 offset0:16 offset1:20
	v_add_u32_e32 v15, s62, v172
	v_add_u32_e32 v175, s62, v173
	ds_read2st64_b64 v[184:187], v15 offset0:16 offset1:20
	ds_read2st64_b64 v[188:191], v175 offset0:16 offset1:20
	s_waitcnt lgkmcnt(0)
	v_mov_b32_e32 v182, v176
	v_mov_b32_e32 v183, v177
	v_mov_b32_e32 v176, v12
	v_mov_b32_e32 v177, v13
	v_mov_b32_e32 v180, v10
	v_mov_b32_e32 v181, v11
	v_mfma_f32_32x32x16_bf16 v[64:79], v[176:179], v[2:5], v[64:79]
	ds_read2st64_b64 v[10:13], v0 offset0:24 offset1:28
	ds_read2st64_b64 v[176:179], v14 offset0:24 offset1:28
	v_mov_b32_e32 v194, v188
	v_mov_b32_e32 v195, v189
	v_mov_b32_e32 v188, v186
	v_mov_b32_e32 v189, v187
	v_mov_b32_e32 v192, v184
	v_mov_b32_e32 v193, v185
	v_mfma_f32_32x32x16_bf16 v[80:95], v[180:183], v[2:5], v[80:95]
	s_waitcnt lgkmcnt(0)
	v_mov_b32_e32 v180, v10
	v_mov_b32_e32 v181, v11
	v_mov_b32_e32 v182, v176
	v_mov_b32_e32 v183, v177
	v_mov_b32_e32 v176, v12
	v_mov_b32_e32 v177, v13
	ds_read2st64_b64 v[184:187], v15 offset0:24 offset1:28
	v_mfma_f32_32x32x16_bf16 v[64:79], v[188:191], v[6:9], v[64:79]
	ds_read2st64_b64 v[188:191], v175 offset0:24 offset1:28
	v_mfma_f32_32x32x16_bf16 v[48:63], v[180:183], v[2:5], v[48:63]
	v_mfma_f32_32x32x16_bf16 v[32:47], v[176:179], v[2:5], v[32:47]
	v_mfma_f32_32x32x16_bf16 v[80:95], v[192:195], v[6:9], v[80:95]
	s_waitcnt lgkmcnt(0)
	v_mov_b32_e32 v192, v184
	v_mov_b32_e32 v193, v185
	v_mov_b32_e32 v194, v188
	v_mov_b32_e32 v195, v189
	v_mov_b32_e32 v188, v186
	v_mov_b32_e32 v189, v187
	v_mfma_f32_32x32x16_bf16 v[48:63], v[192:195], v[6:9], v[48:63]
	s_nop 0
	v_mfma_f32_32x32x16_bf16 v[32:47], v[188:191], v[6:9], v[32:47]
	s_branch .LBB0_553

; DI void xcd_barrier(const XcdBarrier& b) {
;     asm volatile("s_waitcnt vmcnt(0)" ::: "memory");
;     __syncthreads();
;     if (threadIdx.x == 0) {
;         unsigned* bar = b.bar;
;         __builtin_amdgcn_s_waitcnt(0);
;         unsigned nloc = b.st[0], nx = b.st[1];
;         if (nloc == 0u) { xcd_barrier_complete(bar, b.x, nloc, nx); b.st[0] = nloc; b.st[1] = nx; }
.LBB0_562:
	s_setprio 0
	s_waitcnt vmcnt(0)
	s_barrier
	s_mov_b64 s[2:3], exec
	v_readlane_b32 s0, v236, 0
	v_readlane_b32 s1, v236, 1
	s_and_b64 s[0:1], s[2:3], s[0:1]
	s_mov_b64 exec, s[0:1]
	s_cbranch_execz .LBB0_614
	s_add_i32 s0, 0, 0x27ff0
	v_mov_b32_e32 v0, s0
	s_waitcnt vmcnt(0) expcnt(0) lgkmcnt(0)
	ds_read_b32 v2, v0
	s_add_i32 s0, 0, 0x27ff4
	v_mov_b32_e32 v0, s0
	ds_read_b32 v0, v0
	s_waitcnt lgkmcnt(1)
	v_cmp_ne_u32_e32 vcc, 0, v2
	s_cbranch_vccnz .LBB0_578
	s_add_u32 s4, s30, 0x3f732200
	s_addc_u32 s5, s31, 0
	s_add_u32 s8, s30, 0x3f732400
	s_addc_u32 s9, s31, 0
	s_add_u32 s16, s30, 0x3f732500
	s_addc_u32 s17, s31, 0
	s_add_u32 s18, s30, 0x3f732600
	s_addc_u32 s19, s31, 0
	s_add_u32 s20, s30, 0x3f732700
	s_addc_u32 s21, s31, 0
	s_add_u32 s22, s30, 0x3f732800
	s_addc_u32 s23, s31, 0
	s_add_u32 s24, s30, 0x3f732900
	s_addc_u32 s25, s31, 0
	s_add_u32 s26, s30, 0x3f732a00
	s_addc_u32 s27, s31, 0
	s_add_u32 s36, s30, 0x3f732b00
	s_addc_u32 s37, s31, 0
	s_add_u32 s38, s30, 0x3f732c00
	s_addc_u32 s39, s31, 0
	s_add_u32 s40, s30, 0x3f732d00
	s_addc_u32 s41, s31, 0
	s_add_u32 s42, s30, 0x3f732e00
	s_addc_u32 s43, s31, 0
	s_add_u32 s44, s30, 0x3f732f00
	s_addc_u32 s45, s31, 0
	s_add_u32 s46, s30, 0x3f733000
	s_addc_u32 s47, s31, 0
	s_add_u32 s48, s30, 0x3f733100
	s_addc_u32 s49, s31, 0
	s_add_u32 s50, s30, 0x3f733200
	s_addc_u32 s51, s31, 0
	s_mul_i32 s33, s11, s87
	s_add_u32 s52, s30, 0x3f733300
	s_mul_i32 s33, s33, s10
	s_addc_u32 s53, s31, 0
	s_mov_b32 s60, 1
	v_mov_b32_e32 v16, 0
	s_branch .LBB0_566
